# P1: bias and first row-statistics loads of the epilogue issued at unit start into spare registers
# baseline (speedup 1.0000x reference)
.Lnr_p1:
	s_lshl_b32 s98, s15, 8
	s_lshl_b32 s99, s15, 7
	s_addk_i32 s99, 0x700
	s_cmp_gt_u32 s15, 13
	s_movk_i32 s100, 0x2000
	s_cselect_b32 s98, s99, s98
	s_cselect_b32 s100, s100, 0x200
	v_add_u32_e32 v100, s98, v244
	v_ashrrev_i32_e32 v101, 31, v100
	v_lshl_add_u64 v[100:101], v[100:101], 2, s[8:9]
	s_mov_b32 s98, s100
	s_mov_b32 s99, 0
	v_lshl_add_u64 v[102:103], v[100:101], 0, s[98:99]
	global_load_dwordx4 v[84:87], v[100:101], off
	global_load_dwordx4 v[88:91], v[100:101], off offset:16
	global_load_dwordx4 v[92:95], v[102:103], off
	global_load_dwordx4 v[96:99], v[102:103], off offset:16
	s_lshl_b32 s98, s14, 11
	s_add_u32 s98, s71, s98
	s_addc_u32 s99, s72, 0
	v_lshl_add_u64 v[102:103], s[98:99], 0, v[186:187]
	global_load_dwordx2 v[100:101], v[102:103], off
	s_add_i32 s82, s82, 1
	v_readlane_b32 s0, v250, 2
	s_lshl_b32 s1, s82, 8
	s_add_i32 s1, s1, s0
	s_cmp_lt_u32 s1, 0x780
	s_cselect_b64 s[40:41], -1, 0
	s_lshl_b32 s1, s82, 5
	s_lshr_b32 s6, s0, 3
	s_add_i32 s1, s1, s6
	s_and_b32 s0, s0, 7
	s_lshl_b32 s0, s0, 3
	s_cmp_ge_u32 s1, 0x78
	s_cselect_b32 s6, 0x78, 0
	s_cselect_b32 s85, 4, 0
	s_sub_i32 s1, s1, s6
	s_add_i32 s85, s85, s0
	s_and_b32 s0, s1, 3
	s_add_i32 s85, s85, s0
	s_lshr_b32 s84, s1, 2

.LBB0_158:
	s_xor_b64 s[48:49], s[0:1], -1
	s_cmpk_gt_i32 s88, 0x3ff
	s_cselect_b64 s[28:29], -1, 0
	s_lshl_b32 s19, s14, 11
	s_add_i32 s4, s88, 0xe00
	s_and_b64 s[0:1], s[0:1], exec
	s_cselect_b32 s0, s4, s18
	v_add_u32_e32 v16, s0, v244
	s_movk_i32 s0, 0x2000
	v_ashrrev_i32_e32 v17, 31, v16
	s_cselect_b32 s34, s0, 0x200
	s_cmp_lt_i32 s15, 5
	v_lshl_add_u64 v[20:21], v[16:17], 2, s[8:9]
	s_cselect_b64 s[0:1], -1, 0
	v_lshl_add_u64 v[28:29], v[20:21], 0, s[34:35]
	s_and_b64 s[4:5], s[12:13], s[0:1]
	s_lshl_b32 s34, s14, 8
	s_add_u32 s0, s71, s19
	s_addc_u32 s1, s72, 0
	s_mov_b64 s[18:19], s[0:1]
	v_mov_b32_e32 v16, v88
	v_mov_b32_e32 v17, v89
	v_mov_b32_e32 v18, v90
	v_mov_b32_e32 v19, v91
	v_mov_b32_e32 v24, v84
	v_mov_b32_e32 v25, v85
	v_mov_b32_e32 v26, v86
	v_mov_b32_e32 v27, v87
	s_nop 0
	v_mov_b32_e32 v20, v96
	v_mov_b32_e32 v21, v97
	v_mov_b32_e32 v22, v98
	v_mov_b32_e32 v23, v99
	s_nop 0
	v_mov_b32_e32 v28, v92
	v_mov_b32_e32 v29, v93
	v_mov_b32_e32 v30, v94
	v_mov_b32_e32 v31, v95
	v_mul_lo_u32 v80, s89, v82
	v_lshl_add_u64 v[152:153], s[18:19], 0, v[186:187]
	s_add_u32 s18, s0, 0x80
	s_addc_u32 s19, s1, 0
	v_mov_b32_e32 v152, v100
	v_mov_b32_e32 v153, v101
	v_or_b32_e32 v80, v80, v244
	v_lshl_add_u64 v[154:155], s[18:19], 0, v[186:187]
	s_add_u32 s18, s0, 0x100
	s_addc_u32 s19, s1, 0
	global_load_dwordx2 v[204:205], v[154:155], off
	v_lshlrev_b32_e32 v80, 1, v80
	v_lshl_add_u64 v[154:155], s[18:19], 0, v[186:187]
	s_add_u32 s18, s0, 0x180
	s_addc_u32 s19, s1, 0
	global_load_dwordx2 v[202:203], v[154:155], off
	s_and_b64 vcc, exec, s[10:11]
	s_cbranch_vccz .Lab_p1
	s_barrier
